# v034 + P0b RMSNorm rows loop writes H's tiled image in full 128-B lines (row pair halves exchanged with DPP)
# baseline (speedup 1.0000x reference)
; template <int NR> __device__ __forceinline__ void rms_rows_to_bf16(const float* xbase, const float* gain, bf16_t* obase, int row_off, int m0, int mstride, int mend, int lane) {
;     f32x4 v[NR][8]; float s[NR];
; #pragma unroll
;     for (int r = 0; r < NR; ++r) { const int m = m0 + r * mstride; s[r] = 0.f;
;         if (m < mend) { const f32x4* xr = (const f32x4*)(xbase + (size_t)m * DMODEL) + lane;
; #pragma unroll
;             for (int j = 0; j < 8; ++j) v[r][j] = __builtin_nontemporal_load(xr + 64 * j); }
;         else {
; #pragma unroll
;             for (int j = 0; j < 8; ++j) v[r][j] = (f32x4){0.f, 0.f, 0.f, 0.f}; } }
;     const f32x4* gr = (const f32x4*)gain + lane;
; #pragma unroll
;     for (int r = 0; r < NR; ++r) { const int m = m0 + r * mstride;
; #pragma unroll
;         for (int j = 0; j < 8; ++j) s[r] += (v[r][j][0] * v[r][j][0] + v[r][j][1] * v[r][j][1]) + (v[r][j][2] * v[r][j][2] + v[r][j][3] * v[r][j][3]);
;         const float rr = 1.0f / sqrtf(wave_sum(s[r]) * (1.0f / DMODEL) + EPS);
.Lp0b_chk_done:
	s_cmpk_gt_i32 s12, 0x1fff
	s_cbranch_scc1 .LBB0_119
	v_mbcnt_lo_u32_b32 v2, -1, 0
	v_mbcnt_hi_u32_b32 v2, -1, v2
	v_and_b32_e32 v3, 64, v2
	v_add_u32_e32 v3, 64, v3
	v_xor_b32_e32 v4, 1, v2
	v_cmp_lt_i32_e32 vcc, v4, v3
	v_lshlrev_b32_e32 v46, 4, v255
	v_mov_b32_e32 v47, 0
	v_cndmask_b32_e32 v4, v2, v4, vcc
	v_lshlrev_b32_e32 v78, 2, v4
	v_xor_b32_e32 v4, 2, v2
	v_cmp_lt_i32_e32 vcc, v4, v3
	v_lshl_add_u64 v[50:51], s[56:57], 0, v[46:47]
	s_mov_b64 s[0:1], 0x1000
	v_cndmask_b32_e32 v4, v2, v4, vcc
	v_lshlrev_b32_e32 v79, 2, v4
	v_xor_b32_e32 v4, 4, v2
	v_cmp_lt_i32_e32 vcc, v4, v3
	v_lshl_add_u64 v[52:53], v[50:51], 0, s[0:1]
	s_mov_b64 s[0:1], 0x1400
	v_cndmask_b32_e32 v4, v2, v4, vcc
	v_lshlrev_b32_e32 v80, 2, v4
	v_xor_b32_e32 v4, 8, v2
	v_cmp_lt_i32_e32 vcc, v4, v3
	v_lshl_add_u64 v[54:55], v[50:51], 0, s[0:1]
	s_mov_b64 s[0:1], 0x1800
	v_cndmask_b32_e32 v4, v2, v4, vcc
	v_lshlrev_b32_e32 v81, 2, v4
	v_xor_b32_e32 v4, 16, v2
	v_cmp_lt_i32_e32 vcc, v4, v3
	v_lshl_add_u64 v[56:57], v[50:51], 0, s[0:1]
	s_mov_b64 s[0:1], 0x1c00
	v_cndmask_b32_e32 v4, v2, v4, vcc
	v_lshlrev_b32_e32 v82, 2, v4
	v_xor_b32_e32 v4, 32, v2
	v_cmp_lt_i32_e32 vcc, v4, v3
	v_lshl_add_u64 v[58:59], v[50:51], 0, s[0:1]
	s_lshl_b32 s0, s2, 4
	v_cndmask_b32_e32 v2, v2, v4, vcc
	v_lshlrev_b32_e32 v83, 2, v2
	v_lshlrev_b32_e32 v2, 9, v0
	s_lshl_b32 s1, s33, 1
	v_and_b32_e32 v2, 0x6000, v2
	s_add_i32 s0, s0, s1
	v_or_b32_e32 v4, 0x8000, v2
	v_or_b32_e32 v6, 0x10000, v2
	v_or_b32_e32 v8, 0x18000, v2
	v_or_b32_e32 v10, 0x20000, v2
	v_or_b32_e32 v12, 0x28000, v2
	v_or_b32_e32 v14, 0x30000, v2
	v_or_b32_e32 v16, 0x38000, v2
	s_add_i32 s4, s0, 0xfffffe01
	s_lshl_b32 s10, s3, 4
	s_lshl_b32 s0, s2, 10
	s_lshl_b32 s1, s33, 7
	s_lshl_b32 s14, s3, 10
	v_lshl_add_u64 v[48:49], s[52:53], 0, v[46:47]
	v_bfe_u32 v84, v0, 3, 1
	v_and_b32_e32 v1, 56, v1
	s_addk_i32 s10, 0xfe00
	s_add_i32 s11, s0, s1
	s_addk_i32 s14, 0x8000
	s_movk_i32 s15, 0x1000
	v_mov_b32_e32 v85, 0x358637bd
	s_mov_b32 s16, 0xf800000
	v_mov_b32_e32 v86, 0x260
	v_lshlrev_b32_e32 v60, 1, v2
	v_mov_b32_e32 v61, v47
	v_lshlrev_b32_e32 v62, 1, v4
	v_mov_b32_e32 v63, v47
	v_lshlrev_b32_e32 v64, 1, v6
	v_mov_b32_e32 v65, v47
	v_lshlrev_b32_e32 v66, 1, v8
	v_mov_b32_e32 v67, v47
	v_lshlrev_b32_e32 v68, 1, v10
	v_mov_b32_e32 v69, v47
	v_lshlrev_b32_e32 v70, 1, v12
	v_mov_b32_e32 v71, v47
	v_lshlrev_b32_e32 v72, 1, v14
	v_mov_b32_e32 v73, v47
	v_lshlrev_b32_e32 v74, 1, v16
	v_mov_b32_e32 v75, v47
	v_bfe_u32 v160, v255, 3, 1
	v_mul_u32_u24_e32 v161, 0x3c0, v160
	v_mov_b32_e32 v164, 0xffffffc0
	v_sub_u32_e32 v164, v164, v161
	v_mov_b32_e32 v165, -1
	v_sub_u32_e32 v166, 0x3c0, v161
	v_mov_b32_e32 v167, 0
.LBB0_118:
	s_add_i32 s0, s4, -1
	s_ashr_i32 s5, s4, 31
	s_ashr_i32 s1, s0, 31
	s_lshl_b64 s[18:19], s[4:5], 13
	s_lshr_b32 s5, s0, 3
	s_lshl_b64 s[0:1], s[0:1], 13
	v_lshl_add_u64 v[2:3], v[48:49], 0, s[18:19]
	v_lshl_add_u64 v[4:5], v[48:49], 0, s[0:1]
	global_load_dwordx4 v[88:91], v[50:51], off
	global_load_dwordx4 v[30:33], v[2:3], off nt
	global_load_dwordx4 v[26:29], v[2:3], off offset:1024 nt
	global_load_dwordx4 v[22:25], v[2:3], off offset:2048 nt
	global_load_dwordx4 v[14:17], v[2:3], off offset:3072 nt
	global_load_dwordx4 v[92:95], v[4:5], off nt
	global_load_dwordx4 v[96:99], v[4:5], off offset:1024 nt
	global_load_dwordx4 v[100:103], v[4:5], off offset:2048 nt
	global_load_dwordx4 v[104:107], v[4:5], off offset:3072 nt
	v_add_co_u32_e32 v4, vcc, 0x1000, v4
	s_ashr_i32 s6, s12, 6
	s_nop 0
	v_addc_co_u32_e32 v5, vcc, 0, v5, vcc
	global_load_dwordx4 v[108:111], v[4:5], off nt
	global_load_dwordx4 v[42:45], v[4:5], off offset:1024 nt
	global_load_dwordx4 v[38:41], v[4:5], off offset:2048 nt
	global_load_dwordx4 v[34:37], v[4:5], off offset:3072 nt
	s_add_i32 s17, s11, 0xffff8000
	s_ashr_i32 s7, s6, 31
	s_and_b32 s20, s17, 0x380
	s_lshr_b32 s17, s17, 4
	v_and_or_b32 v6, s5, 14, v84
	s_and_b32 s5, s17, 32
	s_lshl_b64 s[6:7], s[6:7], 19
	v_or_b32_e32 v7, s20, v1
	v_lshlrev_b32_e32 v87, 10, v6
	s_add_u32 s6, s30, s6
	v_bitop3_b32 v46, v87, v7, s5 bitop3:0xf6
	s_addc_u32 s7, s31, s7
	v_lshl_add_u64 v[76:77], s[6:7], 0, v[46:47]
	v_add_co_u32_e32 v2, vcc, s15, v2
	v_lshl_add_u64 v[112:113], v[76:77], 0, v[60:61]
	s_nop 0
	v_addc_co_u32_e32 v3, vcc, 0, v3, vcc
	global_load_dwordx4 v[18:21], v[2:3], off nt
	global_load_dwordx4 v[10:13], v[2:3], off offset:1024 nt
	global_load_dwordx4 v[6:9], v[2:3], off offset:2048 nt
	s_nop 0
	global_load_dwordx4 v[2:5], v[2:3], off offset:3072 nt
	s_add_i32 s12, s12, s13
	s_add_i32 s4, s4, s10
	s_waitcnt vmcnt(11)
	v_mul_f32_e32 v46, v93, v93
	v_mul_f32_e32 v114, v95, v95
	s_waitcnt vmcnt(10)
	v_mul_f32_e32 v115, v97, v97
	v_mul_f32_e32 v116, v99, v99
	s_waitcnt vmcnt(9)
	v_mul_f32_e32 v117, v101, v101
	v_mul_f32_e32 v118, v103, v103
	v_fmac_f32_e32 v46, v92, v92
	v_fmac_f32_e32 v114, v94, v94
	v_fmac_f32_e32 v115, v96, v96
	v_fmac_f32_e32 v116, v98, v98
	s_waitcnt vmcnt(8)
	v_mul_f32_e32 v119, v105, v105
	v_mul_f32_e32 v120, v107, v107
	v_fmac_f32_e32 v117, v100, v100
	v_fmac_f32_e32 v118, v102, v102
	v_add_f32_e32 v46, v46, v114
	v_add_f32_e32 v114, v115, v116
	v_fmac_f32_e32 v119, v104, v104
	v_fmac_f32_e32 v120, v106, v106
	v_add_f32_e32 v115, v117, v118
	s_waitcnt vmcnt(7)
	v_mul_f32_e32 v117, v109, v109
	v_mul_f32_e32 v118, v111, v111
	v_add_f32_e32 v46, v46, v114
	v_add_f32_e32 v116, v119, v120
	s_waitcnt vmcnt(6)
	v_mul_f32_e32 v119, v43, v43
	v_mul_f32_e32 v120, v45, v45
	v_fmac_f32_e32 v117, v108, v108
	v_fmac_f32_e32 v118, v110, v110
	v_add_f32_e32 v46, v46, v115
	s_waitcnt vmcnt(5)
; __host__ __device__ __forceinline__ size_t img_off(int r, int c, int K) { return ((size_t)(r >> 7) * (size_t)(K >> 6) + (size_t)(c >> 6)) * 8192u + (size_t)(lds_byte(r & 127, c & 63) >> 1); }
; __device__ __forceinline__ unsigned cvt_pk_bf16(float lo, float hi) { unsigned r; asm volatile("v_cvt_pk_bf16_f32 %0, %1, %2" : "=v"(r) : "v"(lo), "v"(hi)); return r; }
; template <int NR> __device__ __forceinline__ void rms_rows_to_bf16(const float* xbase, const float* gain, bf16_t* obase, int row_off, int m0, int mstride, int mend, int lane) {
;     ...
;     for (int r = 0; r < NR; ++r) { const int m = m0 + r * mstride;
; #pragma unroll
;         for (int j = 0; j < 8; ++j) s[r] += (v[r][j][0] * v[r][j][0] + v[r][j][1] * v[r][j][1]) + (v[r][j][2] * v[r][j][2] + v[r][j][3] * v[r][j][3]);
;         const float rr = 1.0f / sqrtf(wave_sum(s[r]) * (1.0f / DMODEL) + EPS);
;         if (m < mend) {
; #pragma unroll
;             for (int j = 0; j < 8; ++j) { const f32x4 g = gr[64 * j]; u32x2 w; w.x = cvt_pk_bf16(v[r][j][0] * rr * g[0], v[r][j][1] * rr * g[1]); w.y = cvt_pk_bf16(v[r][j][2] * rr * g[2], v[r][j][3] * rr * g[3]);
;                 *(u32x2*)(obase + pg8::img_off(row_off + m, 4 * (lane + 64 * j), DMODEL)) = w; } } }
	v_mul_f32_e32 v121, v39, v39
	v_mul_f32_e32 v122, v41, v41
	v_fmac_f32_e32 v119, v42, v42
	v_fmac_f32_e32 v120, v44, v44
	v_add_f32_e32 v114, v117, v118
	v_add_f32_e32 v46, v46, v116
	s_waitcnt vmcnt(4)
	v_mul_f32_e32 v123, v35, v35
	v_mul_f32_e32 v124, v37, v37
	v_fmac_f32_e32 v121, v38, v38
	v_fmac_f32_e32 v122, v40, v40
	v_add_f32_e32 v115, v119, v120
	v_add_f32_e32 v46, v46, v114
	v_fmac_f32_e32 v123, v34, v34
	v_fmac_f32_e32 v124, v36, v36
	v_add_f32_e32 v117, v121, v122
	v_add_f32_e32 v46, v46, v115
	v_add_f32_e32 v118, v123, v124
	v_add_f32_e32 v46, v46, v117
	v_add_f32_e32 v46, v46, v118
	ds_bpermute_b32 v114, v78, v46
	s_waitcnt lgkmcnt(0)
	v_add_f32_e32 v46, v46, v114
	ds_bpermute_b32 v114, v79, v46
	s_waitcnt lgkmcnt(0)
	v_add_f32_e32 v46, v46, v114
	ds_bpermute_b32 v114, v80, v46
	s_waitcnt lgkmcnt(0)
	v_add_f32_e32 v46, v46, v114
	ds_bpermute_b32 v114, v81, v46
	s_waitcnt lgkmcnt(0)
	v_add_f32_e32 v46, v46, v114
	ds_bpermute_b32 v114, v82, v46
	s_waitcnt lgkmcnt(0)
	v_add_f32_e32 v46, v46, v114
	ds_bpermute_b32 v114, v83, v46
	s_waitcnt lgkmcnt(0)
	v_add_f32_e32 v46, v46, v114
	v_fmamk_f32 v46, v46, 0x3a000000, v85
	v_mul_f32_e32 v114, 0x4f800000, v46
	v_cmp_gt_f32_e32 vcc, s16, v46
	s_nop 1
	v_cndmask_b32_e32 v46, v46, v114, vcc
	v_sqrt_f32_e32 v114, v46
	s_nop 0
	v_add_u32_e32 v115, -1, v114
	v_add_u32_e32 v116, 1, v114
	v_fma_f32 v117, -v115, v114, v46
	v_fma_f32 v118, -v116, v114, v46
	v_cmp_ge_f32_e64 s[0:1], 0, v117
	s_nop 1
	v_cndmask_b32_e64 v114, v114, v115, s[0:1]
	v_cmp_lt_f32_e64 s[0:1], 0, v118
	s_nop 1
	v_cndmask_b32_e64 v114, v114, v116, s[0:1]
	v_mul_f32_e32 v115, 0x37800000, v114
	v_cndmask_b32_e32 v114, v114, v115, vcc
	v_cmp_class_f32_e32 vcc, v46, v86
	s_nop 1
	v_cndmask_b32_e32 v46, v114, v46, vcc
	v_div_scale_f32 v114, s[0:1], v46, v46, 1.0
	v_rcp_f32_e32 v116, v114
	v_div_scale_f32 v115, vcc, 1.0, v46, 1.0
	s_add_i32 s0, s11, 0xffff8040
	v_fma_f32 v117, -v114, v116, 1.0
	v_fmac_f32_e32 v116, v117, v116
	v_mul_f32_e32 v117, v115, v116
	v_fma_f32 v118, -v114, v117, v115
	v_fmac_f32_e32 v117, v118, v116
	v_fma_f32 v114, -v114, v117, v115
	v_div_fmas_f32 v114, v114, v116, v117
	v_div_fixup_f32 v114, v114, v46, 1.0
	v_mul_f32_e32 v46, v92, v114
	v_mul_f32_e32 v92, v93, v114
	v_mul_f32_e32 v93, v94, v114
	v_mul_f32_e32 v94, v95, v114
	v_mul_f32_e32 v46, v88, v46
	v_mul_f32_e32 v88, v89, v92
	v_mul_f32_e32 v89, v90, v93
	v_mul_f32_e32 v90, v91, v94
	v_cvt_pk_bf16_f32 v88, v46, v88
	v_cvt_pk_bf16_f32 v89, v89, v90
	v_mov_b32_e32 v168, v88
	v_mov_b32_e32 v169, v89
	global_load_dwordx4 v[88:91], v[50:51], off offset:1024
	v_mul_f32_e32 v46, v96, v114
	v_mul_f32_e32 v94, v97, v114
	v_mul_f32_e32 v95, v98, v114
	v_lshl_add_u64 v[92:93], v[76:77], 0, v[62:63]
	v_mul_f32_e32 v96, v99, v114
	v_mul_f32_e32 v42, v42, v114
	v_mul_f32_e32 v43, v43, v114
	v_mul_f32_e32 v44, v44, v114
	v_mul_f32_e32 v45, v45, v114
	v_mul_f32_e32 v38, v38, v114
	v_mul_f32_e32 v39, v39, v114
	v_mul_f32_e32 v40, v40, v114
	v_mul_f32_e32 v41, v41, v114
	v_mul_f32_e32 v34, v34, v114
	v_mul_f32_e32 v35, v35, v114
	v_mul_f32_e32 v36, v36, v114
	v_mul_f32_e32 v37, v37, v114
	s_and_b32 s1, s0, 0x3c0
	s_lshr_b32 s0, s0, 4
	s_and_b32 s0, s0, 32
	s_add_i32 s11, s11, s14
	s_cmpk_lt_i32 s12, 0x2000
	s_waitcnt vmcnt(0)
	v_mul_f32_e32 v46, v88, v46
	v_mul_f32_e32 v88, v89, v94
	v_mul_f32_e32 v89, v90, v95
	v_mul_f32_e32 v90, v91, v96
	v_cvt_pk_bf16_f32 v88, v46, v88
	v_cvt_pk_bf16_f32 v89, v89, v90
	v_mov_b32_e32 v170, v88
	v_mov_b32_e32 v171, v89
	global_load_dwordx4 v[88:91], v[50:51], off offset:2048
	v_mul_f32_e32 v46, v100, v114
	v_mul_f32_e32 v94, v101, v114
	v_mul_f32_e32 v95, v102, v114
	v_lshl_add_u64 v[92:93], v[76:77], 0, v[64:65]
	v_mul_f32_e32 v96, v103, v114
	v_mul_f32_e32 v100, v27, v27
	v_fmac_f32_e32 v100, v26, v26
	v_mul_f32_e32 v101, v5, v5
	v_fmac_f32_e32 v101, v4, v4
	s_waitcnt vmcnt(0)
	v_mul_f32_e32 v46, v46, v88
	v_mul_f32_e32 v88, v94, v89
	v_mul_f32_e32 v89, v95, v90
	v_mul_f32_e32 v90, v96, v91
	v_cvt_pk_bf16_f32 v88, v46, v88
	v_cvt_pk_bf16_f32 v89, v89, v90
	v_mov_b32_e32 v172, v88
	v_mov_b32_e32 v173, v89
	global_load_dwordx4 v[88:91], v[50:51], off offset:3072
	v_mul_f32_e32 v46, v104, v114
	v_mul_f32_e32 v94, v105, v114
	v_mul_f32_e32 v95, v106, v114
	v_lshl_add_u64 v[92:93], v[76:77], 0, v[66:67]
	v_mul_f32_e32 v96, v107, v114
	s_waitcnt vmcnt(0)
	v_mul_f32_e32 v46, v46, v88
	v_mul_f32_e32 v88, v94, v89
	v_mul_f32_e32 v89, v95, v90
	v_mul_f32_e32 v90, v96, v91
	v_cvt_pk_bf16_f32 v88, v46, v88
	v_cvt_pk_bf16_f32 v89, v89, v90
	v_mov_b32_e32 v174, v88
	v_mov_b32_e32 v175, v89
	global_load_dwordx4 v[88:91], v[52:53], off
	v_mul_f32_e32 v46, v108, v114
	v_mul_f32_e32 v94, v109, v114
	v_mul_f32_e32 v95, v110, v114
	v_lshl_add_u64 v[92:93], v[76:77], 0, v[68:69]
	v_mul_f32_e32 v96, v111, v114
	s_waitcnt vmcnt(0)
	v_mul_f32_e32 v46, v46, v88
	v_mul_f32_e32 v88, v94, v89
	v_mul_f32_e32 v89, v95, v90
	v_mul_f32_e32 v90, v96, v91
	v_cvt_pk_bf16_f32 v88, v46, v88
	v_cvt_pk_bf16_f32 v89, v89, v90
	v_mov_b32_e32 v176, v88
	v_mov_b32_e32 v177, v89
	global_load_dwordx4 v[88:91], v[54:55], off
	v_lshl_add_u64 v[92:93], v[76:77], 0, v[70:71]
	v_lshl_add_u64 v[94:95], v[76:77], 0, v[72:73]
	v_lshl_add_u64 v[96:97], v[76:77], 0, v[74:75]
	v_or_b32_e32 v46, s1, v1
	v_bitop3_b32 v46, v46, v87, s0 bitop3:0xde
	v_lshl_add_u64 v[76:77], s[6:7], 0, v[46:47]
	v_mul_f32_e32 v46, v31, v31
	v_mul_f32_e32 v87, v33, v33
	v_fmac_f32_e32 v46, v30, v30
	v_fmac_f32_e32 v87, v32, v32
	v_add_f32_e32 v46, v46, v87
	v_lshl_add_u64 v[98:99], v[76:77], 0, v[60:61]
	s_waitcnt vmcnt(0)
; __host__ __device__ __forceinline__ size_t img_off(int r, int c, int K) { return ((size_t)(r >> 7) * (size_t)(K >> 6) + (size_t)(c >> 6)) * 8192u + (size_t)(lds_byte(r & 127, c & 63) >> 1); }
; __device__ __forceinline__ unsigned cvt_pk_bf16(float lo, float hi) { unsigned r; asm volatile("v_cvt_pk_bf16_f32 %0, %1, %2" : "=v"(r) : "v"(lo), "v"(hi)); return r; }
; template <int NR> __device__ __forceinline__ void rms_rows_to_bf16(const float* xbase, const float* gain, bf16_t* obase, int row_off, int m0, int mstride, int mend, int lane) {
;     ...
;     for (int r = 0; r < NR; ++r) { const int m = m0 + r * mstride;
; #pragma unroll
;         for (int j = 0; j < 8; ++j) s[r] += (v[r][j][0] * v[r][j][0] + v[r][j][1] * v[r][j][1]) + (v[r][j][2] * v[r][j][2] + v[r][j][3] * v[r][j][3]);
;         const float rr = 1.0f / sqrtf(wave_sum(s[r]) * (1.0f / DMODEL) + EPS);
;         if (m < mend) {
; #pragma unroll
;             for (int j = 0; j < 8; ++j) { const f32x4 g = gr[64 * j]; u32x2 w; w.x = cvt_pk_bf16(v[r][j][0] * rr * g[0], v[r][j][1] * rr * g[1]); w.y = cvt_pk_bf16(v[r][j][2] * rr * g[2], v[r][j][3] * rr * g[3]);
;                 *(u32x2*)(obase + pg8::img_off(row_off + m, 4 * (lane + 64 * j), DMODEL)) = w; } } }
	v_mul_f32_e32 v42, v42, v88
	v_mul_f32_e32 v43, v43, v89
	v_mul_f32_e32 v44, v44, v90
	v_mul_f32_e32 v45, v45, v91
	v_cvt_pk_bf16_f32 v42, v42, v43
	v_cvt_pk_bf16_f32 v43, v44, v45
	v_mov_b32_e32 v178, v42
	v_mov_b32_e32 v179, v43
	global_load_dwordx4 v[42:45], v[56:57], off
	v_mul_f32_e32 v88, v29, v29
	v_mul_f32_e32 v89, v23, v23
	v_mul_f32_e32 v90, v25, v25
	v_fmac_f32_e32 v88, v28, v28
	v_fmac_f32_e32 v89, v22, v22
	v_fmac_f32_e32 v90, v24, v24
	v_add_f32_e32 v87, v100, v88
	v_mul_f32_e32 v91, v15, v15
	v_mul_f32_e32 v92, v17, v17
	v_add_f32_e32 v88, v89, v90
	v_add_f32_e32 v46, v46, v87
	v_fmac_f32_e32 v91, v14, v14
	v_fmac_f32_e32 v92, v16, v16
	v_add_f32_e32 v46, v46, v88
	v_mul_f32_e32 v87, v19, v19
	v_mul_f32_e32 v88, v21, v21
	v_add_f32_e32 v89, v91, v92
	v_mul_f32_e32 v90, v11, v11
	v_mul_f32_e32 v91, v13, v13
	v_fmac_f32_e32 v87, v18, v18
	v_fmac_f32_e32 v88, v20, v20
	v_mul_f32_e32 v92, v7, v7
	v_mul_f32_e32 v93, v9, v9
	v_add_f32_e32 v46, v46, v89
	v_fmac_f32_e32 v90, v10, v10
	v_fmac_f32_e32 v91, v12, v12
	v_mul_f32_e32 v100, v3, v3
	v_fmac_f32_e32 v92, v6, v6
	v_fmac_f32_e32 v93, v8, v8
	v_fmac_f32_e32 v100, v2, v2
	s_waitcnt vmcnt(0)
	v_mul_f32_e32 v38, v38, v42
	v_mul_f32_e32 v39, v39, v43
	v_mul_f32_e32 v40, v40, v44
	v_mul_f32_e32 v41, v41, v45
	v_cvt_pk_bf16_f32 v38, v38, v39
	v_cvt_pk_bf16_f32 v39, v40, v41
	v_mov_b32_e32 v180, v38
	v_mov_b32_e32 v181, v39
	global_load_dwordx4 v[38:41], v[58:59], off
	v_add_f32_e32 v42, v87, v88
	v_add_f32_e32 v43, v90, v91
	v_add_f32_e32 v42, v46, v42
	v_add_f32_e32 v44, v92, v93
	v_add_f32_e32 v42, v42, v43
	v_add_f32_e32 v45, v100, v101
	v_add_f32_e32 v42, v42, v44
	v_add_f32_e32 v42, v42, v45
	ds_bpermute_b32 v43, v78, v42
	s_waitcnt lgkmcnt(0)
	v_add_f32_e32 v42, v42, v43
	ds_bpermute_b32 v43, v79, v42
	s_waitcnt lgkmcnt(0)
	v_add_f32_e32 v42, v42, v43
	ds_bpermute_b32 v43, v80, v42
	s_waitcnt lgkmcnt(0)
	v_add_f32_e32 v42, v42, v43
	ds_bpermute_b32 v43, v81, v42
	s_waitcnt lgkmcnt(0)
	v_add_f32_e32 v42, v42, v43
	ds_bpermute_b32 v43, v82, v42
	s_waitcnt lgkmcnt(0)
	v_add_f32_e32 v42, v42, v43
	s_waitcnt vmcnt(0)
	v_mul_f32_e32 v34, v34, v38
	v_mul_f32_e32 v35, v35, v39
	v_mul_f32_e32 v36, v36, v40
	v_mul_f32_e32 v37, v37, v41
	v_cvt_pk_bf16_f32 v34, v34, v35
	v_cvt_pk_bf16_f32 v35, v36, v37
	v_mov_b32_e32 v182, v34
	v_mov_b32_e32 v183, v35
	global_load_dwordx4 v[34:37], v[50:51], off
	ds_bpermute_b32 v38, v83, v42
	s_waitcnt lgkmcnt(0)
	v_add_f32_e32 v38, v42, v38
	v_fmamk_f32 v38, v38, 0x3a000000, v85
	v_mul_f32_e32 v39, 0x4f800000, v38
	v_cmp_gt_f32_e32 vcc, s16, v38
	s_nop 1
	v_cndmask_b32_e32 v38, v38, v39, vcc
	v_sqrt_f32_e32 v39, v38
	s_nop 0
	v_add_u32_e32 v40, -1, v39
	v_add_u32_e32 v41, 1, v39
	v_fma_f32 v42, -v40, v39, v38
	v_fma_f32 v43, -v41, v39, v38
	v_cmp_ge_f32_e64 s[0:1], 0, v42
	s_nop 1
	v_cndmask_b32_e64 v39, v39, v40, s[0:1]
	v_cmp_lt_f32_e64 s[0:1], 0, v43
	s_nop 1
	v_cndmask_b32_e64 v39, v39, v41, s[0:1]
	v_mul_f32_e32 v40, 0x37800000, v39
	v_cndmask_b32_e32 v39, v39, v40, vcc
	v_cmp_class_f32_e32 vcc, v38, v86
	s_nop 1
	v_cndmask_b32_e32 v38, v39, v38, vcc
	v_div_scale_f32 v39, s[0:1], v38, v38, 1.0
	v_rcp_f32_e32 v41, v39
	v_div_scale_f32 v40, vcc, 1.0, v38, 1.0
	v_fma_f32 v42, -v39, v41, 1.0
	v_fmac_f32_e32 v41, v42, v41
	v_mul_f32_e32 v42, v40, v41
	v_fma_f32 v43, -v39, v42, v40
	v_fmac_f32_e32 v42, v43, v41
	v_fma_f32 v39, -v39, v42, v40
	v_div_fmas_f32 v39, v39, v41, v42
	v_div_fixup_f32 v38, v39, v38, 1.0
	v_mul_f32_e32 v30, v30, v38
	v_mul_f32_e32 v31, v31, v38
	v_mul_f32_e32 v32, v32, v38
	v_mul_f32_e32 v33, v33, v38
	v_mul_f32_e32 v26, v26, v38
	v_mul_f32_e32 v27, v27, v38
	v_mul_f32_e32 v28, v28, v38
	v_mul_f32_e32 v29, v29, v38
	v_mul_f32_e32 v22, v22, v38
	v_mul_f32_e32 v23, v23, v38
	v_mul_f32_e32 v24, v24, v38
	v_mul_f32_e32 v25, v25, v38
	v_mul_f32_e32 v14, v14, v38
	v_mul_f32_e32 v15, v15, v38
	v_mul_f32_e32 v16, v16, v38
	v_mul_f32_e32 v17, v17, v38
	v_mul_f32_e32 v18, v18, v38
	v_mul_f32_e32 v19, v19, v38
	v_mul_f32_e32 v20, v20, v38
	v_mul_f32_e32 v21, v21, v38
	v_mul_f32_e32 v10, v10, v38
	v_mul_f32_e32 v11, v11, v38
	v_mul_f32_e32 v12, v12, v38
	v_mul_f32_e32 v13, v13, v38
	v_mul_f32_e32 v6, v6, v38
	v_mul_f32_e32 v7, v7, v38
	v_mul_f32_e32 v8, v8, v38
	v_mul_f32_e32 v9, v9, v38
	v_mul_f32_e32 v2, v2, v38
	v_mul_f32_e32 v3, v3, v38
	v_mul_f32_e32 v4, v4, v38
	s_waitcnt vmcnt(0)
	v_mul_f32_e32 v30, v34, v30
	v_mul_f32_e32 v31, v35, v31
	v_mul_f32_e32 v32, v36, v32
	v_mul_f32_e32 v33, v37, v33
	v_cvt_pk_bf16_f32 v30, v30, v31
	v_cvt_pk_bf16_f32 v31, v32, v33
	v_mov_b32_e32 v160, v30
	v_mov_b32_e32 v161, v31
	v_lshl_add_u64 v[162:163], v[98:99], 0, v[164:165]
	v_mov_b32_dpp v30, v168 row_shl:8 row_mask:0xf bank_mask:0x3
	v_mov_b32_dpp v31, v169 row_shl:8 row_mask:0xf bank_mask:0x3
	v_mov_b32_dpp v168, v160 row_shr:8 row_mask:0xf bank_mask:0xc
	v_mov_b32_dpp v169, v161 row_shr:8 row_mask:0xf bank_mask:0xc
	global_store_dwordx2 v[162:163], v[168:169], off
	v_lshl_add_u64 v[162:163], v[98:99], 0, v[166:167]
	global_store_dwordx2 v[162:163], v[30:31], off
	global_load_dwordx4 v[30:33], v[50:51], off offset:1024
	v_lshl_add_u64 v[34:35], v[76:77], 0, v[62:63]
	v_mul_f32_e32 v5, v5, v38
	s_waitcnt vmcnt(0)
; __host__ __device__ __forceinline__ size_t img_off(int r, int c, int K) { return ((size_t)(r >> 7) * (size_t)(K >> 6) + (size_t)(c >> 6)) * 8192u + (size_t)(lds_byte(r & 127, c & 63) >> 1); }
; __device__ __forceinline__ unsigned cvt_pk_bf16(float lo, float hi) { unsigned r; asm volatile("v_cvt_pk_bf16_f32 %0, %1, %2" : "=v"(r) : "v"(lo), "v"(hi)); return r; }
; template <int NR> __device__ __forceinline__ void rms_rows_to_bf16(const float* xbase, const float* gain, bf16_t* obase, int row_off, int m0, int mstride, int mend, int lane) {
;     ...
;         if (m < mend) {
; #pragma unroll
;             for (int j = 0; j < 8; ++j) { const f32x4 g = gr[64 * j]; u32x2 w; w.x = cvt_pk_bf16(v[r][j][0] * rr * g[0], v[r][j][1] * rr * g[1]); w.y = cvt_pk_bf16(v[r][j][2] * rr * g[2], v[r][j][3] * rr * g[3]);
;                 *(u32x2*)(obase + pg8::img_off(row_off + m, 4 * (lane + 64 * j), DMODEL)) = w; } } }
	v_mul_f32_e32 v26, v30, v26
	v_mul_f32_e32 v27, v31, v27
	v_mul_f32_e32 v28, v32, v28
	v_mul_f32_e32 v29, v33, v29
	v_cvt_pk_bf16_f32 v26, v26, v27
	v_cvt_pk_bf16_f32 v27, v28, v29
	v_mov_b32_e32 v160, v26
	v_mov_b32_e32 v161, v27
	v_lshl_add_u64 v[162:163], v[34:35], 0, v[164:165]
	v_mov_b32_dpp v26, v170 row_shl:8 row_mask:0xf bank_mask:0x3
	v_mov_b32_dpp v27, v171 row_shl:8 row_mask:0xf bank_mask:0x3
	v_mov_b32_dpp v170, v160 row_shr:8 row_mask:0xf bank_mask:0xc
	v_mov_b32_dpp v171, v161 row_shr:8 row_mask:0xf bank_mask:0xc
	global_store_dwordx2 v[162:163], v[170:171], off
	v_lshl_add_u64 v[162:163], v[34:35], 0, v[166:167]
	global_store_dwordx2 v[162:163], v[26:27], off
	global_load_dwordx4 v[26:29], v[50:51], off offset:2048
	v_lshl_add_u64 v[30:31], v[76:77], 0, v[64:65]
	s_waitcnt vmcnt(0)
	v_mul_f32_e32 v22, v22, v26
	v_mul_f32_e32 v23, v23, v27
	v_mul_f32_e32 v24, v24, v28
	v_mul_f32_e32 v25, v25, v29
	v_cvt_pk_bf16_f32 v22, v22, v23
	v_cvt_pk_bf16_f32 v23, v24, v25
	v_mov_b32_e32 v160, v22
	v_mov_b32_e32 v161, v23
	v_lshl_add_u64 v[162:163], v[30:31], 0, v[164:165]
	v_mov_b32_dpp v22, v172 row_shl:8 row_mask:0xf bank_mask:0x3
	v_mov_b32_dpp v23, v173 row_shl:8 row_mask:0xf bank_mask:0x3
	v_mov_b32_dpp v172, v160 row_shr:8 row_mask:0xf bank_mask:0xc
	v_mov_b32_dpp v173, v161 row_shr:8 row_mask:0xf bank_mask:0xc
	global_store_dwordx2 v[162:163], v[172:173], off
	v_lshl_add_u64 v[162:163], v[30:31], 0, v[166:167]
	global_store_dwordx2 v[162:163], v[22:23], off
	global_load_dwordx4 v[22:25], v[50:51], off offset:3072
	v_lshl_add_u64 v[26:27], v[76:77], 0, v[66:67]
	s_waitcnt vmcnt(0)
	v_mul_f32_e32 v14, v14, v22
	v_mul_f32_e32 v15, v15, v23
	v_mul_f32_e32 v16, v16, v24
	v_mul_f32_e32 v17, v17, v25
	v_cvt_pk_bf16_f32 v14, v14, v15
	v_cvt_pk_bf16_f32 v15, v16, v17
	v_mov_b32_e32 v160, v14
	v_mov_b32_e32 v161, v15
	v_lshl_add_u64 v[162:163], v[26:27], 0, v[164:165]
	v_mov_b32_dpp v14, v174 row_shl:8 row_mask:0xf bank_mask:0x3
	v_mov_b32_dpp v15, v175 row_shl:8 row_mask:0xf bank_mask:0x3
	v_mov_b32_dpp v174, v160 row_shr:8 row_mask:0xf bank_mask:0xc
	v_mov_b32_dpp v175, v161 row_shr:8 row_mask:0xf bank_mask:0xc
	global_store_dwordx2 v[162:163], v[174:175], off
	v_lshl_add_u64 v[162:163], v[26:27], 0, v[166:167]
	global_store_dwordx2 v[162:163], v[14:15], off
	global_load_dwordx4 v[14:17], v[52:53], off
	v_lshl_add_u64 v[22:23], v[76:77], 0, v[68:69]
	s_waitcnt vmcnt(0)
	v_mul_f32_e32 v14, v18, v14
	v_mul_f32_e32 v15, v19, v15
	v_mul_f32_e32 v16, v20, v16
	v_mul_f32_e32 v17, v21, v17
	v_cvt_pk_bf16_f32 v14, v14, v15
	v_cvt_pk_bf16_f32 v15, v16, v17
	v_mov_b32_e32 v160, v14
	v_mov_b32_e32 v161, v15
	v_lshl_add_u64 v[162:163], v[22:23], 0, v[164:165]
	v_mov_b32_dpp v14, v176 row_shl:8 row_mask:0xf bank_mask:0x3
	v_mov_b32_dpp v15, v177 row_shl:8 row_mask:0xf bank_mask:0x3
	v_mov_b32_dpp v176, v160 row_shr:8 row_mask:0xf bank_mask:0xc
	v_mov_b32_dpp v177, v161 row_shr:8 row_mask:0xf bank_mask:0xc
	global_store_dwordx2 v[162:163], v[176:177], off
	v_lshl_add_u64 v[162:163], v[22:23], 0, v[166:167]
	global_store_dwordx2 v[162:163], v[14:15], off
	global_load_dwordx4 v[14:17], v[54:55], off
	v_lshl_add_u64 v[18:19], v[76:77], 0, v[70:71]
	s_waitcnt vmcnt(0)
	v_mul_f32_e32 v10, v10, v14
	v_mul_f32_e32 v11, v11, v15
	v_mul_f32_e32 v12, v12, v16
	v_mul_f32_e32 v13, v13, v17
	v_cvt_pk_bf16_f32 v10, v10, v11
	v_cvt_pk_bf16_f32 v11, v12, v13
	v_mov_b32_e32 v160, v10
	v_mov_b32_e32 v161, v11
	v_lshl_add_u64 v[162:163], v[18:19], 0, v[164:165]
	v_mov_b32_dpp v10, v178 row_shl:8 row_mask:0xf bank_mask:0x3
	v_mov_b32_dpp v11, v179 row_shl:8 row_mask:0xf bank_mask:0x3
	v_mov_b32_dpp v178, v160 row_shr:8 row_mask:0xf bank_mask:0xc
	v_mov_b32_dpp v179, v161 row_shr:8 row_mask:0xf bank_mask:0xc
	global_store_dwordx2 v[162:163], v[178:179], off
	v_lshl_add_u64 v[162:163], v[18:19], 0, v[166:167]
	global_store_dwordx2 v[162:163], v[10:11], off
	global_load_dwordx4 v[10:13], v[56:57], off
	v_lshl_add_u64 v[14:15], v[76:77], 0, v[72:73]
	s_waitcnt vmcnt(0)
	v_mul_f32_e32 v6, v6, v10
	v_mul_f32_e32 v7, v7, v11
	v_mul_f32_e32 v8, v8, v12
	v_mul_f32_e32 v9, v9, v13
	v_cvt_pk_bf16_f32 v6, v6, v7
	v_cvt_pk_bf16_f32 v7, v8, v9
	v_mov_b32_e32 v160, v6
	v_mov_b32_e32 v161, v7
	v_lshl_add_u64 v[162:163], v[14:15], 0, v[164:165]
	v_mov_b32_dpp v6, v180 row_shl:8 row_mask:0xf bank_mask:0x3
	v_mov_b32_dpp v7, v181 row_shl:8 row_mask:0xf bank_mask:0x3
	v_mov_b32_dpp v180, v160 row_shr:8 row_mask:0xf bank_mask:0xc
	v_mov_b32_dpp v181, v161 row_shr:8 row_mask:0xf bank_mask:0xc
	global_store_dwordx2 v[162:163], v[180:181], off
	v_lshl_add_u64 v[162:163], v[14:15], 0, v[166:167]
	global_store_dwordx2 v[162:163], v[6:7], off
	global_load_dwordx4 v[6:9], v[58:59], off
	v_lshl_add_u64 v[10:11], v[76:77], 0, v[74:75]
	s_waitcnt vmcnt(0)
	v_mul_f32_e32 v2, v2, v6
	v_mul_f32_e32 v3, v3, v7
	v_mul_f32_e32 v4, v4, v8
	v_mul_f32_e32 v5, v5, v9
	v_cvt_pk_bf16_f32 v2, v2, v3
	v_cvt_pk_bf16_f32 v3, v4, v5
	v_mov_b32_e32 v160, v2
	v_mov_b32_e32 v161, v3
	v_lshl_add_u64 v[162:163], v[10:11], 0, v[164:165]
	v_mov_b32_dpp v2, v182 row_shl:8 row_mask:0xf bank_mask:0x3
	v_mov_b32_dpp v3, v183 row_shl:8 row_mask:0xf bank_mask:0x3
	v_mov_b32_dpp v182, v160 row_shr:8 row_mask:0xf bank_mask:0xc
	v_mov_b32_dpp v183, v161 row_shr:8 row_mask:0xf bank_mask:0xc
	global_store_dwordx2 v[162:163], v[182:183], off
	v_lshl_add_u64 v[162:163], v[10:11], 0, v[166:167]
	global_store_dwordx2 v[162:163], v[2:3], off
	s_cbranch_scc1 .LBB0_118
